# E24: gate phase (P2a): Ws fragments, bias and U pieces of a unit issued together at the iteration top into unused VGPRs; next-unit prefetch unconditional; counted waits exact; loop-top wait leaves sto
# baseline (speedup 1.0000x reference)
.LBB0_402:
	v_readlane_b32 s8, v251, 5
	v_readlane_b32 s22, v251, 19
	v_readlane_b32 s23, v251, 20
	s_add_u32 s0, s22, 1.0
	s_addc_u32 s1, s23, 0
	s_cmp_lt_i32 s96, 4
	s_cselect_b64 s[2:3], -1, 0
	s_cmp_gt_i32 s97, 3
	s_cselect_b64 s[4:5], -1, 0
	s_and_b64 s[2:3], s[2:3], s[4:5]
	s_andn2_b64 vcc, exec, s[2:3]
	v_readlane_b32 s9, v251, 6
	v_readlane_b32 s10, v251, 7
	v_readlane_b32 s11, v251, 8
	v_readlane_b32 s12, v251, 9
	v_readlane_b32 s13, v251, 10
	v_readlane_b32 s14, v251, 11
	v_readlane_b32 s15, v251, 12
	v_readlane_b32 s16, v251, 13
	v_readlane_b32 s17, v251, 14
	v_readlane_b32 s18, v251, 15
	v_readlane_b32 s19, v251, 16
	v_readlane_b32 s20, v251, 17
	v_readlane_b32 s21, v251, 18
	s_cbranch_vccnz .LBB0_606
	v_readlane_b32 s2, v251, 0
	s_and_b32 s10, s2, 0xffffffc0
	v_readlane_b32 s5, v251, 4
	s_cmpk_lt_i32 s5, 0x800
	v_readlane_b32 s4, v251, 42
	s_cselect_b64 s[2:3], -1, 0
	s_lshl_b32 s11, s4, 4
	s_lshl_b32 s48, s5, 3
	s_cmpk_gt_i32 s5, 0x7ff
	v_mbcnt_lo_u32_b32 v16, -1, 0
	v_mbcnt_hi_u32_b32 v16, -1, v16
	s_cbranch_scc1 .LBB0_410
	v_add_u32_e32 v0, s10, v16
	v_ashrrev_i32_e32 v1, 4, v0
	v_lshlrev_b32_e32 v2, 2, v1
	v_and_b32_e32 v17, 15, v16
	v_and_b32_e32 v2, 12, v2
	v_bfe_u32 v3, v1, 2, 2
	v_bitop3_b32 v2, v2, v17, v3 bitop3:0x36
	v_lshlrev_b32_e32 v43, 4, v2
	v_add_u32_e32 v2, 0x200, v0
	v_ashrrev_i32_e32 v2, 4, v2
	v_readlane_b32 s12, v251, 5
	v_lshlrev_b32_e32 v3, 2, v2
	v_readlane_b32 s20, v251, 13
	v_readlane_b32 s21, v251, 14
	v_readlane_b32 s22, v251, 15
	v_readlane_b32 s23, v251, 16
	v_readlane_b32 s24, v251, 17
	v_readlane_b32 s25, v251, 18
	v_and_b32_e32 v3, 12, v3
	v_bfe_u32 v4, v2, 2, 2
	v_readlane_b32 s26, v251, 19
	v_readlane_b32 s27, v251, 20
	s_mov_b64 s[20:21], s[24:25]
	v_bitop3_b32 v3, v3, v17, v4 bitop3:0x36
	v_readlane_b32 s14, v251, 7
	s_mov_b64 s[22:23], s[26:27]
	v_lshlrev_b32_e32 v45, 4, v3
	v_add_u32_e32 v3, 0x400, v0
	s_add_u32 s14, s22, 0x2f800000
	v_ashrrev_i32_e32 v3, 4, v3
	s_addc_u32 s20, s23, 0
	v_lshlrev_b32_e32 v4, 2, v3
	s_and_b32 s4, s48, 0xffffff80
	v_and_b32_e32 v4, 12, v4
	v_bfe_u32 v5, v3, 2, 2
	v_add_u32_e32 v0, 0x600, v0
	s_ashr_i32 s5, s4, 31
	v_bitop3_b32 v4, v4, v17, v5 bitop3:0x36
	v_ashrrev_i32_e32 v0, 4, v0
	s_lshl_b64 s[4:5], s[4:5], 12
	v_lshlrev_b32_e32 v47, 4, v4
	v_lshlrev_b32_e32 v4, 2, v0
	s_add_u32 s4, s14, s4
	v_readlane_b32 s24, v251, 4
	v_and_b32_e32 v4, 12, v4
	v_bfe_u32 v5, v0, 2, 2
	s_addc_u32 s5, s20, s5
	s_lshl_b32 s6, s24, 8
	v_bitop3_b32 v4, v4, v17, v5 bitop3:0x36
	s_lshl_b32 s35, s24, 7
	s_and_b32 s6, s6, 0xf00
	v_lshlrev_b32_e32 v49, 4, v4
	s_add_u32 s4, s4, s6
	v_lshlrev_b32_e32 v4, 3, v17
	v_mov_b32_e32 v29, 0
	s_addc_u32 s5, s5, 0
	v_lshl_or_b32 v20, v0, 11, v4
	v_lshl_or_b32 v22, v3, 11, v4
	v_lshl_or_b32 v24, v2, 11, v4
	v_lshl_or_b32 v26, v1, 11, v4
	v_mov_b32_e32 v27, v29
	v_mov_b32_e32 v25, v29
	v_mov_b32_e32 v23, v29
	v_mov_b32_e32 v21, v29
	v_lshlrev_b32_e32 v42, 8, v1
	v_lshlrev_b32_e32 v48, 8, v0
	v_lshl_add_u64 v[0:1], v[26:27], 1, s[4:5]
	v_lshl_add_u64 v[4:5], v[24:25], 1, s[4:5]
	v_lshl_add_u64 v[8:9], v[22:23], 1, s[4:5]
	v_lshl_add_u64 v[12:13], v[20:21], 1, s[4:5]
	v_lshlrev_b32_e32 v44, 8, v2
	v_lshlrev_b32_e32 v46, 8, v3
	global_load_dwordx4 v[0:3], v[0:1], off
	s_nop 0
	global_load_dwordx4 v[4:7], v[4:5], off
	s_nop 0
	global_load_dwordx4 v[8:11], v[8:9], off
	s_nop 0
	global_load_dwordx4 v[12:15], v[12:13], off
	v_ashrrev_i32_e32 v28, 4, v16
	v_lshlrev_b32_e32 v34, 1, v28
	v_bfe_u32 v19, v16, 2, 2
	v_lshlrev_b32_e32 v18, 3, v28
	v_and_b32_e32 v31, 12, v16
	v_lshlrev_b32_e32 v32, 3, v16
	v_and_b32_e32 v34, 2, v34
	v_bfe_u32 v30, v16, 1, 1
	v_and_b32_e32 v32, 8, v32
	v_or_b32_e32 v33, v18, v19
	v_or_b32_e32 v35, v34, v31
	v_lshl_or_b32 v33, v33, 8, v32
	v_or_b32_e32 v35, v35, v30
	v_lshl_or_b32 v50, v35, 4, v33
	v_or_b32_e32 v35, 2, v30
	v_bitop3_b32 v36, v34, v35, v31 bitop3:0x36
	v_lshl_or_b32 v51, v36, 4, v33
	v_or_b32_e32 v36, 4, v30
	v_bitop3_b32 v37, v34, v36, v31 bitop3:0x36
	v_lshl_or_b32 v52, v37, 4, v33
	v_or_b32_e32 v37, 6, v30
	v_bitop3_b32 v38, v34, v37, v31 bitop3:0x36
	v_lshl_or_b32 v53, v38, 4, v33
	v_or_b32_e32 v38, 8, v30
	v_bitop3_b32 v39, v34, v38, v31 bitop3:0x36
	v_lshl_or_b32 v54, v39, 4, v33
	v_or_b32_e32 v39, 10, v30
	v_bitop3_b32 v40, v34, v39, v31 bitop3:0x36
	v_lshl_or_b32 v55, v40, 4, v33
	v_or_b32_e32 v40, 12, v30
	v_bitop3_b32 v41, v34, v40, v31 bitop3:0x36
	v_lshl_or_b32 v56, v41, 4, v33
	v_or_b32_e32 v41, 14, v30
	v_bitop3_b32 v34, v34, v41, v31 bitop3:0x36
	v_lshl_or_b32 v57, v34, 4, v33
	v_or_b32_e32 v33, 4, v18
	v_or_b32_e32 v19, v33, v19
	v_bfe_u32 v33, v33, 2, 2
	v_lshl_or_b32 v19, v19, 8, v32
	v_bitop3_b32 v30, v33, v30, v31 bitop3:0x36
	v_lshl_or_b32 v58, v30, 4, v19
	v_bitop3_b32 v30, v33, v35, v31 bitop3:0x36
	v_lshl_or_b32 v59, v30, 4, v19
	v_bitop3_b32 v30, v33, v36, v31 bitop3:0x36
	v_lshl_or_b32 v60, v30, 4, v19
	v_bitop3_b32 v30, v33, v37, v31 bitop3:0x36
	v_lshl_or_b32 v61, v30, 4, v19
	v_bitop3_b32 v30, v33, v38, v31 bitop3:0x36
	v_lshl_or_b32 v62, v30, 4, v19
	v_bitop3_b32 v30, v33, v39, v31 bitop3:0x36
	v_lshl_or_b32 v63, v30, 4, v19
	v_bitop3_b32 v30, v33, v40, v31 bitop3:0x36
	v_lshl_or_b32 v64, v30, 4, v19
	v_bitop3_b32 v30, v33, v41, v31 bitop3:0x36
	v_readlane_b32 s68, v251, 21
	v_lshl_or_b32 v65, v30, 4, v19
	v_readlane_b32 s72, v251, 25
	v_readlane_b32 s73, v251, 26
	v_ashrrev_i32_e32 v19, 31, v18
	v_readlane_b32 s74, v251, 27
	v_readlane_b32 s75, v251, 28
	s_mov_b64 s[40:41], s[72:73]
	v_lshl_add_u64 v[18:19], v[18:19], 1, s[22:23]
	s_mov_b64 s[6:7], 0x400000
	v_lshlrev_b32_e32 v32, 2, v28
	v_mov_b32_e32 v34, s40
	v_mov_b32_e32 v35, s41
	v_or_b32_e32 v66, s11, v17
	v_lshl_add_u64 v[30:31], v[18:19], 0, s[6:7]
	v_ashrrev_i32_e32 v33, 31, v32
	v_and_b32_e32 v18, 8, v32
	v_and_b32_e32 v16, 16, v16
	v_readlane_b32 s4, v251, 3
	v_mbcnt_lo_u32_b32 v17, -1, 0
	s_mov_b32 s5, 0
	v_lshl_add_u64 v[34:35], v[32:33], 2, v[34:35]
	s_lshl_b32 s21, s4, 3
	s_lshl_b32 s22, s4, 7
	v_mbcnt_hi_u32_b32 v67, -1, v17
	v_mov_b32_e32 v68, 0x358637bd
	s_mov_b32 s23, 0x800000
	v_lshlrev_b32_e32 v36, 1, v18
	v_lshlrev_b32_e32 v38, 1, v16
	s_mov_b32 s4, s48
	s_mov_b32 s25, 0
	v_readlane_b32 s13, v251, 6
	v_readlane_b32 s15, v251, 8
	v_readlane_b32 s16, v251, 9
	v_readlane_b32 s17, v251, 10
	v_readlane_b32 s18, v251, 11
	v_readlane_b32 s19, v251, 12
	v_readlane_b32 s69, v251, 22
	v_readlane_b32 s70, v251, 23
	v_readlane_b32 s71, v251, 24
	v_readlane_b32 s76, v251, 29
	v_readlane_b32 s77, v251, 30
	v_readlane_b32 s78, v251, 31
	v_readlane_b32 s79, v251, 32
	v_readlane_b32 s80, v251, 33
	v_readlane_b32 s81, v251, 34
	v_readlane_b32 s82, v251, 35
	v_readlane_b32 s83, v251, 36
	s_mov_b64 s[42:43], s[74:75]
	s_waitcnt vmcnt(0)
	s_branch .LBB0_406
.LBB0_405:
	s_and_b32 s8, s35, 0x780
	v_add_u32_e32 v28, s8, v66
	v_lshlrev_b64 v[16:17], 8, v[28:29]
	v_lshl_add_u64 v[40:41], v[30:31], 0, v[16:17]
	v_add_u32_e32 v132, s36, v60
	v_add_u32_e32 v136, s36, v53
	v_add_u32_e32 v148, s36, v61
	v_add_u32_e32 v176, s36, v63
	v_add_u32_e32 v37, s36, v50
	v_add_u32_e32 v39, s36, v58
	v_add_u32_e32 v69, s36, v51
	v_add_u32_e32 v74, s36, v59
	v_add_u32_e32 v75, s36, v52
	v_add_u32_e32 v180, s36, v56
	v_add_u32_e32 v188, s36, v64
	v_add_u32_e32 v192, s36, v57
	v_add_u32_e32 v200, s36, v65
	ds_read_b64_tr_b16 v[76:77], v176
	ds_read_b64_tr_b16 v[78:79], v180
	ds_read_b64_tr_b16 v[80:81], v188
	ds_read_b64_tr_b16 v[82:83], v192
	ds_read_b64_tr_b16 v[84:85], v200
	ds_read_b64_tr_b16 v[86:87], v37
	ds_read_b64_tr_b16 v[90:91], v37 offset:8192
	ds_read_b64_tr_b16 v[94:95], v37 offset:16384
	ds_read_b64_tr_b16 v[98:99], v37 offset:24576
	ds_read_b64_tr_b16 v[88:89], v39
	ds_read_b64_tr_b16 v[92:93], v39 offset:8192
	ds_read_b64_tr_b16 v[96:97], v39 offset:16384
	ds_read_b64_tr_b16 v[100:101], v39 offset:24576
	ds_read_b64_tr_b16 v[102:103], v69
	ds_read_b64_tr_b16 v[106:107], v69 offset:8192
	ds_read_b64_tr_b16 v[110:111], v69 offset:16384
	ds_read_b64_tr_b16 v[114:115], v69 offset:24576
	ds_read_b64_tr_b16 v[104:105], v74
	ds_read_b64_tr_b16 v[108:109], v74 offset:8192
	ds_read_b64_tr_b16 v[112:113], v74 offset:16384
	ds_read_b64_tr_b16 v[116:117], v74 offset:24576
	ds_read_b64_tr_b16 v[118:119], v75
	ds_read_b64_tr_b16 v[122:123], v75 offset:8192
	ds_read_b64_tr_b16 v[126:127], v75 offset:16384
	ds_read_b64_tr_b16 v[130:131], v75 offset:24576
	ds_read_b64_tr_b16 v[120:121], v132
	ds_read_b64_tr_b16 v[124:125], v132 offset:8192
	ds_read_b64_tr_b16 v[128:129], v132 offset:16384
	ds_read_b64_tr_b16 v[132:133], v132 offset:24576
	ds_read_b64_tr_b16 v[134:135], v136
	ds_read_b64_tr_b16 v[138:139], v136 offset:8192
	ds_read_b64_tr_b16 v[142:143], v136 offset:16384
	ds_read_b64_tr_b16 v[146:147], v136 offset:24576
	ds_read_b64_tr_b16 v[136:137], v148
	ds_read_b64_tr_b16 v[140:141], v148 offset:8192
	ds_read_b64_tr_b16 v[144:145], v148 offset:16384
	ds_read_b64_tr_b16 v[148:149], v148 offset:24576
	v_add_u32_e32 v152, s36, v54
	v_add_u32_e32 v164, s36, v62
	v_add_u32_e32 v168, s36, v55
	ds_read_b64_tr_b16 v[150:151], v152
	ds_read_b64_tr_b16 v[154:155], v152 offset:8192
	ds_read_b64_tr_b16 v[158:159], v152 offset:16384
	ds_read_b64_tr_b16 v[162:163], v152 offset:24576
	ds_read_b64_tr_b16 v[152:153], v164
	ds_read_b64_tr_b16 v[156:157], v164 offset:8192
	ds_read_b64_tr_b16 v[160:161], v164 offset:16384
	ds_read_b64_tr_b16 v[164:165], v164 offset:24576
	ds_read_b64_tr_b16 v[74:75], v168
	ds_read_b64_tr_b16 v[166:167], v168 offset:8192
	ds_read_b64_tr_b16 v[170:171], v168 offset:16384
	ds_read_b64_tr_b16 v[174:175], v168 offset:24576
	ds_read_b64_tr_b16 v[168:169], v176 offset:8192
	ds_read_b64_tr_b16 v[172:173], v176 offset:16384
	ds_read_b64_tr_b16 v[176:177], v176 offset:24576
	ds_read_b64_tr_b16 v[178:179], v180 offset:8192
	ds_read_b64_tr_b16 v[182:183], v180 offset:16384
	ds_read_b64_tr_b16 v[186:187], v180 offset:24576
	ds_read_b64_tr_b16 v[180:181], v188 offset:8192
	ds_read_b64_tr_b16 v[184:185], v188 offset:16384
	ds_read_b64_tr_b16 v[188:189], v188 offset:24576
	ds_read_b64_tr_b16 v[190:191], v192 offset:8192
	ds_read_b64_tr_b16 v[194:195], v192 offset:16384
	ds_read_b64_tr_b16 v[198:199], v192 offset:24576
	ds_read_b64_tr_b16 v[192:193], v200 offset:8192
	ds_read_b64_tr_b16 v[196:197], v200 offset:16384
	ds_read_b64_tr_b16 v[200:201], v200 offset:24576
	s_and_b32 s4, s4, 0xffffff80
	v_readlane_b32 s12, v250, 0
	v_readlane_b32 s13, v250, 1
	s_mov_b32 s9, s5
	s_xor_b32 s25, s25, 1
	s_mov_b32 s35, s34
	s_waitcnt vmcnt(13) lgkmcnt(14)
	v_mfma_f32_16x16x32_bf16 v[86:89], v[86:89], v[202:205], 0
	v_mfma_f32_16x16x32_bf16 v[118:121], v[118:121], v[202:205], 0
	v_mfma_f32_16x16x32_bf16 v[102:105], v[102:105], v[202:205], 0
	v_mfma_f32_16x16x32_bf16 v[134:137], v[134:137], v[202:205], 0
	v_mfma_f32_16x16x32_bf16 v[150:153], v[150:153], v[202:205], 0
	v_mfma_f32_16x16x32_bf16 v[74:77], v[74:77], v[202:205], 0
	v_mfma_f32_16x16x32_bf16 v[78:81], v[78:81], v[202:205], 0
	v_mfma_f32_16x16x32_bf16 v[16:19], v[82:85], v[202:205], 0
	s_nop 0
	v_mfma_f32_16x16x32_bf16 v[82:85], v[90:93], v[206:209], v[86:89]
	v_mfma_f32_16x16x32_bf16 v[90:93], v[122:125], v[206:209], v[118:121]
	s_nop 2
	v_mfma_f32_16x16x32_bf16 v[86:89], v[106:109], v[206:209], v[102:105]
	v_mfma_f32_16x16x32_bf16 v[102:105], v[138:141], v[206:209], v[134:137]
	v_mfma_f32_16x16x32_bf16 v[106:109], v[154:157], v[206:209], v[150:153]
	v_mfma_f32_16x16x32_bf16 v[74:77], v[166:169], v[206:209], v[74:77]
	s_waitcnt lgkmcnt(8)
	v_mfma_f32_16x16x32_bf16 v[78:81], v[178:181], v[206:209], v[78:81]
	s_waitcnt lgkmcnt(2)
	v_mfma_f32_16x16x32_bf16 v[16:19], v[190:193], v[206:209], v[16:19]
	s_nop 0
	v_mfma_f32_16x16x32_bf16 v[82:85], v[94:97], v[210:213], v[82:85]
	v_mfma_f32_16x16x32_bf16 v[94:97], v[142:145], v[210:213], v[102:105]
	v_mfma_f32_16x16x32_bf16 v[102:105], v[158:161], v[210:213], v[106:109]
	s_waitcnt lgkmcnt(1)
	v_mfma_f32_16x16x32_bf16 v[106:109], v[194:197], v[210:213], v[16:19]
	s_nop 2
	v_add_u32_e32 v16, s4, v66
	v_ashrrev_i32_e32 v17, 31, v16
	v_lshlrev_b64 v[18:19], 12, v[16:17]
	v_lshl_add_u64 v[18:19], s[12:13], 0, v[18:19]
	s_lshl_b32 s4, s8, 1
	v_lshl_add_u64 v[18:19], v[18:19], 0, s[4:5]
	v_lshl_add_u64 v[40:41], v[32:33], 1, v[18:19]
	v_lshl_add_u64 v[18:19], v[28:29], 2, s[64:65]
	v_mfma_f32_16x16x32_bf16 v[86:89], v[110:113], v[210:213], v[86:89]
	s_lshl_b32 s8, s8, 2
	s_nop 0
	v_mfma_f32_16x16x32_bf16 v[82:85], v[98:101], v[214:217], v[82:85]
	v_lshlrev_b64 v[16:17], 13, v[16:17]
	v_lshl_add_u64 v[16:17], s[0:1], 0, v[16:17]
	v_lshl_add_u64 v[16:17], v[16:17], 0, s[4:5]
	v_mfma_f32_16x16x32_bf16 v[98:101], v[162:165], v[214:217], v[102:105]
	s_mov_b32 s4, s33
	s_waitcnt vmcnt(10)
	s_nop 1
	v_pk_add_f32 v[84:85], v[84:85], v[234:235] op_sel_hi:[1,0]
	v_mfma_f32_16x16x32_bf16 v[86:89], v[114:117], v[214:217], v[86:89]
	v_pk_add_f32 v[82:83], v[82:83], v[234:235] op_sel_hi:[1,0]
	v_mfma_f32_16x16x32_bf16 v[90:93], v[126:129], v[210:213], v[90:93]
	s_nop 3
	v_add_f32_e64 v86, v86, v234
	v_add_f32_e64 v87, v87, v234
	v_pk_add_f32 v[88:89], v[88:89], v[234:235] op_sel_hi:[1,0]
	v_mfma_f32_16x16x32_bf16 v[74:77], v[170:173], v[210:213], v[74:77]
	v_mfma_f32_16x16x32_bf16 v[78:81], v[182:185], v[210:213], v[78:81]
	v_mfma_f32_16x16x32_bf16 v[90:93], v[130:133], v[214:217], v[90:93]
	v_mfma_f32_16x16x32_bf16 v[94:97], v[146:149], v[214:217], v[94:97]
	v_mfma_f32_16x16x32_bf16 v[74:77], v[174:177], v[214:217], v[74:77]
	s_nop 5
	v_add_f32_e64 v92, v92, v234
	v_add_f32_e64 v93, v93, v234
	v_pk_add_f32 v[90:91], v[90:91], v[234:235] op_sel_hi:[1,0]
	v_pk_add_f32 v[94:95], v[94:95], v[234:235] op_sel_hi:[1,0]
	v_mfma_f32_16x16x32_bf16 v[78:81], v[186:189], v[214:217], v[78:81]
	s_waitcnt lgkmcnt(0)
	v_mfma_f32_16x16x32_bf16 v[70:73], v[198:201], v[214:217], v[106:109]
	s_nop 2
	v_lshlrev_b32_e32 v108, 16, v219
	v_and_b32_e32 v109, 0xffff0000, v219
	v_pk_mul_f32 v[108:109], v[84:85], v[108:109]
	v_lshlrev_b32_e32 v106, 16, v218
	v_and_b32_e32 v107, 0xffff0000, v218
	v_pk_mul_f32 v[106:107], v[82:83], v[106:107]
	v_lshlrev_b32_e32 v82, 16, v220
	v_and_b32_e32 v83, 0xffff0000, v220
	v_lshlrev_b32_e32 v110, 16, v221
	v_and_b32_e32 v111, 0xffff0000, v221
	v_pk_mul_f32 v[112:113], v[86:87], v[82:83]
	v_pk_mul_f32 v[110:111], v[88:89], v[110:111]
	v_mov_b32_e32 v86, v107
	v_mov_b32_e32 v87, v113
	v_mov_b32_e32 v82, v106
	v_mov_b32_e32 v83, v112
	v_pk_mul_f32 v[86:87], v[86:87], v[86:87]
	v_mov_b32_e32 v88, v109
	v_mov_b32_e32 v89, v111
	v_pk_fma_f32 v[82:83], v[82:83], v[82:83], v[86:87]
	v_mov_b32_e32 v86, v108
	v_mov_b32_e32 v87, v110
	v_pk_mul_f32 v[88:89], v[88:89], v[88:89]
	s_nop 0
	v_pk_fma_f32 v[86:87], v[86:87], v[86:87], v[88:89]
	s_waitcnt vmcnt(9)
	v_lshlrev_b32_e32 v88, 16, v223
	v_pk_add_f32 v[82:83], v[82:83], v[86:87]
	v_lshlrev_b32_e32 v86, 16, v222
	v_and_b32_e32 v87, 0xffff0000, v222
	v_and_b32_e32 v89, 0xffff0000, v223
	v_pk_mul_f32 v[102:103], v[92:93], v[88:89]
	v_pk_mul_f32 v[118:119], v[90:91], v[86:87]
	v_pk_mul_f32 v[86:87], v[102:103], v[102:103]
	v_pk_mul_f32 v[88:89], v[118:119], v[118:119]
	v_pk_add_f32 v[92:93], v[96:97], v[234:235] op_sel_hi:[1,0]
	v_pk_mov_b32 v[90:91], v[88:89], v[86:87] op_sel:[1,0]
	v_mov_b32_e32 v89, v87
	v_pk_add_f32 v[86:87], v[90:91], v[88:89]
	s_waitcnt vmcnt(8)
	v_lshlrev_b32_e32 v88, 16, v224
	v_and_b32_e32 v89, 0xffff0000, v224
	v_pk_mul_f32 v[120:121], v[94:95], v[88:89]
	s_waitcnt vmcnt(7)
	v_lshlrev_b32_e32 v88, 16, v226
	v_and_b32_e32 v89, 0xffff0000, v226
	v_pk_add_f32 v[94:95], v[98:99], v[234:235] op_sel_hi:[1,0]
	v_lshlrev_b32_e32 v90, 16, v225
	v_and_b32_e32 v91, 0xffff0000, v225
	v_pk_mul_f32 v[122:123], v[94:95], v[88:89]
	v_pk_mul_f32 v[104:105], v[92:93], v[90:91]
	v_pk_add_f32 v[92:93], v[100:101], v[234:235] op_sel_hi:[1,0]
	v_mul_f32_e32 v19, v122, v122
	v_mul_f32_e32 v28, v123, v123
	v_pk_add_f32 v[82:83], v[82:83], v[82:83] op_sel:[0,1] op_sel_hi:[1,0]
	v_pk_add_f32 v[86:87], v[86:87], v[86:87] op_sel:[0,1] op_sel_hi:[1,0]
	v_lshlrev_b32_e32 v90, 16, v227
	v_and_b32_e32 v91, 0xffff0000, v227
	v_mov_b32_e32 v83, v19
	v_mov_b32_e32 v87, v28
	v_mul_f32_e32 v28, v121, v121
	v_pk_mul_f32 v[114:115], v[92:93], v[90:91]
	v_pk_add_f32 v[82:83], v[82:83], v[86:87]
	v_pk_fma_f32 v[86:87], v[120:121], v[120:121], v[28:29] op_sel_hi:[1,1,0]
	v_mul_f32_e32 v28, v105, v105
	v_mul_f32_e32 v37, v114, v114
	v_mul_f32_e32 v39, v115, v115
	v_pk_fma_f32 v[88:89], v[104:105], v[104:105], v[28:29] op_sel_hi:[1,1,0]
	v_mov_b32_e32 v87, v37
	v_mov_b32_e32 v89, v39
	v_pk_add_f32 v[86:87], v[86:87], v[88:89]
	s_waitcnt vmcnt(6)
	v_lshlrev_b32_e32 v88, 16, v229
	v_pk_add_f32 v[86:87], v[82:83], v[86:87]
	v_lshlrev_b32_e32 v82, 16, v228
	v_and_b32_e32 v83, 0xffff0000, v228
	v_and_b32_e32 v89, 0xffff0000, v229
	v_pk_add_f32 v[76:77], v[76:77], v[234:235] op_sel_hi:[1,0]
	v_pk_add_f32 v[74:75], v[74:75], v[234:235] op_sel_hi:[1,0]
	v_pk_mul_f32 v[116:117], v[76:77], v[88:89]
	v_pk_mul_f32 v[124:125], v[74:75], v[82:83]
	v_pk_mul_f32 v[74:75], v[116:117], v[116:117]
	v_pk_mul_f32 v[76:77], v[124:125], v[124:125]
	v_lshl_add_u64 v[98:99], v[34:35], 0, s[8:9]
	v_pk_mov_b32 v[82:83], v[76:77], v[74:75] op_sel:[1,0]
	v_mov_b32_e32 v77, v75
	v_pk_add_f32 v[88:89], v[82:83], v[76:77]
	global_load_dwordx4 v[74:77], v[98:99], off
	s_waitcnt vmcnt(6)
	v_lshlrev_b32_e32 v90, 16, v230
	v_and_b32_e32 v91, 0xffff0000, v230
	v_lshlrev_b32_e32 v92, 16, v231
	v_and_b32_e32 v93, 0xffff0000, v231
	global_load_dwordx4 v[82:85], v[98:99], off offset:64
	v_pk_add_f32 v[78:79], v[78:79], v[234:235] op_sel_hi:[1,0]
	v_pk_add_f32 v[80:81], v[80:81], v[234:235] op_sel_hi:[1,0]
	v_pk_mul_f32 v[128:129], v[78:79], v[90:91]
	s_waitcnt vmcnt(6)
	v_lshlrev_b32_e32 v78, 16, v232
	v_and_b32_e32 v79, 0xffff0000, v232
	v_pk_add_f32 v[72:73], v[72:73], v[234:235] op_sel_hi:[1,0]
	v_pk_add_f32 v[18:19], v[70:71], v[234:235] op_sel_hi:[1,0]
	v_lshlrev_b32_e32 v40, 16, v233
	v_pk_mul_f32 v[130:131], v[18:19], v[78:79]
	v_and_b32_e32 v41, 0xffff0000, v233
	v_mul_f32_e32 v28, v130, v130
	v_mul_f32_e32 v37, v131, v131
	v_pk_add_f32 v[18:19], v[86:87], v[86:87] op_sel:[0,1] op_sel_hi:[1,0]
	v_pk_add_f32 v[86:87], v[88:89], v[88:89] op_sel:[0,1] op_sel_hi:[1,0]
	v_pk_mul_f32 v[126:127], v[80:81], v[92:93]
	v_pk_mul_f32 v[40:41], v[72:73], v[40:41]
	global_load_dwordx4 v[70:73], v[98:99], off offset:128
	global_load_dwordx4 v[78:81], v[98:99], off offset:192
	v_mov_b32_e32 v19, v28
	v_mov_b32_e32 v87, v37
	v_mul_f32_e32 v28, v129, v129
	v_pk_add_f32 v[18:19], v[18:19], v[86:87]
	v_pk_fma_f32 v[86:87], v[128:129], v[128:129], v[28:29] op_sel_hi:[1,1,0]
	v_mul_f32_e32 v28, v127, v127
	v_mul_f32_e32 v39, v40, v40
	v_mul_f32_e32 v69, v41, v41
	v_pk_fma_f32 v[88:89], v[126:127], v[126:127], v[28:29] op_sel_hi:[1,1,0]
	v_mov_b32_e32 v87, v39
	v_mov_b32_e32 v89, v69
	v_pk_add_f32 v[86:87], v[86:87], v[88:89]
	global_load_dwordx4 v[90:93], v[98:99], off offset:320
	v_pk_add_f32 v[18:19], v[18:19], v[86:87]
	global_load_dwordx4 v[86:89], v[98:99], off offset:256
	global_load_dwordx4 v[94:97], v[98:99], off offset:384
	v_and_b32_e32 v28, 64, v67
	global_load_dwordx4 v[98:101], v[98:99], off offset:448
	v_add_f32_e32 v18, v18, v19
	v_xor_b32_e32 v19, 16, v67
	v_add_u32_e32 v28, 64, v28
	v_cmp_lt_i32_e32 vcc, v19, v28
	v_mov_b32_e32 v37, v29
	v_lshl_add_u64 v[132:133], v[16:17], 0, v[36:37]
	v_cndmask_b32_e32 v19, v67, v19, vcc
	v_lshlrev_b32_e32 v19, 2, v19
	ds_bpermute_b32 v19, v19, v18
	v_mov_b32_e32 v39, v29
	s_waitcnt lgkmcnt(0)
	v_add_f32_e32 v18, v18, v19
	v_xor_b32_e32 v19, 32, v67
	v_cmp_lt_i32_e32 vcc, v19, v28
	s_nop 1
	v_cndmask_b32_e32 v19, v67, v19, vcc
	v_lshlrev_b32_e32 v19, 2, v19
	ds_bpermute_b32 v19, v19, v18
	s_waitcnt lgkmcnt(0)
	v_add_f32_e32 v18, v18, v19
	v_fmamk_f32 v18, v18, 0x3c000000, v68
	v_mul_f32_e32 v19, 0x4b800000, v18
	v_cmp_gt_f32_e32 vcc, s23, v18
	s_nop 1
	v_cndmask_b32_e32 v18, v18, v19, vcc
	v_rsq_f32_e32 v18, v18
	s_nop 0
	v_mul_f32_e32 v19, 0x45800000, v18
	v_cndmask_b32_e32 v28, v18, v19, vcc
	v_pk_mul_f32 v[18:19], v[108:109], v[28:29] op_sel_hi:[1,0]
	v_pk_mul_f32 v[16:17], v[106:107], v[28:29] op_sel_hi:[1,0]
	s_waitcnt vmcnt(7)
	v_pk_mul_f32 v[76:77], v[76:77], v[18:19]
	v_pk_mul_f32 v[18:19], v[112:113], v[28:29] op_sel_hi:[1,0]
	v_pk_mul_f32 v[16:17], v[74:75], v[16:17]
	v_pk_mul_f32 v[74:75], v[110:111], v[28:29] op_sel_hi:[1,0]
	s_waitcnt vmcnt(6)
	v_pk_mul_f32 v[18:19], v[82:83], v[18:19]
	v_pk_mul_f32 v[74:75], v[84:85], v[74:75]
	v_cvt_pk_bf16_f32 v16, v16, v17
	v_cvt_pk_bf16_f32 v18, v18, v19
	v_cvt_pk_bf16_f32 v17, v76, v77
	v_pk_mul_f32 v[40:41], v[40:41], v[28:29] op_sel_hi:[1,0]
	v_cvt_pk_bf16_f32 v19, v74, v75
	v_permlane16_swap_b32_e32 v16, v18
	v_permlane16_swap_b32_e32 v17, v19
	v_lshl_add_u64 v[74:75], v[132:133], 0, v[38:39]
	global_store_dwordx4 v[74:75], v[16:19], off
	s_andn2_b64 vcc, exec, s[6:7]
	s_waitcnt vmcnt(1)
	v_pk_mul_f32 v[40:41], v[100:101], v[40:41]
	v_pk_mul_f32 v[18:19], v[102:103], v[28:29] op_sel_hi:[1,0]
	v_pk_mul_f32 v[16:17], v[118:119], v[28:29] op_sel_hi:[1,0]
	v_pk_mul_f32 v[72:73], v[72:73], v[18:19]
	v_pk_mul_f32 v[18:19], v[120:121], v[28:29] op_sel_hi:[1,0]
	v_pk_mul_f32 v[16:17], v[70:71], v[16:17]
	v_pk_mul_f32 v[70:71], v[104:105], v[28:29] op_sel_hi:[1,0]
	v_pk_mul_f32 v[18:19], v[78:79], v[18:19]
	v_pk_mul_f32 v[70:71], v[80:81], v[70:71]
	v_cvt_pk_bf16_f32 v16, v16, v17
	v_cvt_pk_bf16_f32 v18, v18, v19
	v_cvt_pk_bf16_f32 v17, v72, v73
	v_pk_mul_f32 v[72:73], v[116:117], v[28:29] op_sel_hi:[1,0]
	v_cvt_pk_bf16_f32 v19, v70, v71
	v_permlane16_swap_b32_e32 v16, v18
	v_permlane16_swap_b32_e32 v17, v19
	global_store_dwordx4 v[74:75], v[16:19], off offset:64
	v_pk_mul_f32 v[72:73], v[92:93], v[72:73]
	s_nop 0
	v_pk_mul_f32 v[18:19], v[114:115], v[28:29] op_sel_hi:[1,0]
	v_pk_mul_f32 v[16:17], v[122:123], v[28:29] op_sel_hi:[1,0]
	v_pk_mul_f32 v[70:71], v[88:89], v[18:19]
	v_pk_mul_f32 v[18:19], v[124:125], v[28:29] op_sel_hi:[1,0]
	v_pk_mul_f32 v[16:17], v[86:87], v[16:17]
	v_pk_mul_f32 v[18:19], v[90:91], v[18:19]
	v_cvt_pk_bf16_f32 v16, v16, v17
	s_nop 0
	v_cvt_pk_bf16_f32 v18, v18, v19
	v_cvt_pk_bf16_f32 v17, v70, v71
	v_cvt_pk_bf16_f32 v19, v72, v73
	s_nop 0
	v_permlane16_swap_b32_e32 v16, v18
	v_permlane16_swap_b32_e32 v17, v19
	global_store_dwordx4 v[74:75], v[16:19], off offset:128
	s_nop 1
	v_pk_mul_f32 v[18:19], v[126:127], v[28:29] op_sel_hi:[1,0]
	v_pk_mul_f32 v[16:17], v[128:129], v[28:29] op_sel_hi:[1,0]
	v_pk_mul_f32 v[70:71], v[96:97], v[18:19]
	v_pk_mul_f32 v[18:19], v[130:131], v[28:29] op_sel_hi:[1,0]
	v_pk_mul_f32 v[16:17], v[94:95], v[16:17]
	v_pk_mul_f32 v[18:19], v[98:99], v[18:19]
	v_cvt_pk_bf16_f32 v16, v16, v17
	s_nop 0
	v_cvt_pk_bf16_f32 v18, v18, v19
	v_cvt_pk_bf16_f32 v17, v70, v71
	v_cvt_pk_bf16_f32 v19, v40, v41
	s_nop 0
	v_permlane16_swap_b32_e32 v16, v18
	v_permlane16_swap_b32_e32 v17, v19
	global_store_dwordx4 v[74:75], v[16:19], off offset:192
	s_cbranch_vccz .LBB0_410
.LBB0_406:
	s_lshl_b32 s6, s25, 15
	s_add_i32 s36, s6, 0
	v_add3_u32 v16, s36, v43, v42
	s_waitcnt vmcnt(4)
	s_and_b32 s98, s35, 0x780
	v_add_u32_e32 v236, s98, v66
	v_mov_b32_e32 v237, 0
	v_lshlrev_b64 v[238:239], 8, v[236:237]
	v_lshl_add_u64 v[238:239], v[30:31], 0, v[238:239]
	v_lshl_add_u64 v[240:241], v[236:237], 2, s[64:65]
	s_lshl_b32 s98, s98, 1
	s_mov_b32 s99, 0
	s_and_b32 s100, s4, 0xffffff80
	v_add_u32_e32 v242, s100, v66
	v_ashrrev_i32_e32 v243, 31, v242
	v_lshlrev_b64 v[244:245], 12, v[242:243]
	v_readlane_b32 s100, v250, 0
	v_readlane_b32 s101, v250, 1
	global_load_dwordx4 v[202:205], v[238:239], off
	global_load_dwordx4 v[206:209], v[238:239], off offset:64
	global_load_dwordx4 v[210:213], v[238:239], off offset:128
	global_load_dwordx4 v[214:217], v[238:239], off offset:192
	global_load_dword v234, v[240:241], off
	v_lshl_add_u64 v[244:245], s[100:101], 0, v[244:245]
	v_lshl_add_u64 v[244:245], v[244:245], 0, s[98:99]
	v_lshl_add_u64 v[244:245], v[32:33], 1, v[244:245]
	global_load_dwordx2 v[218:219], v[244:245], off
	global_load_dwordx2 v[220:221], v[244:245], off offset:32
	global_load_dwordx2 v[222:223], v[244:245], off offset:64
	global_load_dwordx2 v[224:225], v[244:245], off offset:96
	global_load_dwordx2 v[226:227], v[244:245], off offset:128
	global_load_dwordx2 v[228:229], v[244:245], off offset:160
	global_load_dwordx2 v[230:231], v[244:245], off offset:192
	global_load_dwordx2 v[232:233], v[244:245], off offset:224
	ds_write_b128 v16, v[0:3]
	v_add3_u32 v16, s36, v45, v44
	ds_write_b128 v16, v[4:7]
	v_add3_u32 v16, s36, v47, v46
	ds_write_b128 v16, v[8:11]
	v_add3_u32 v16, s36, v49, v48
	ds_write_b128 v16, v[12:15]
	v_readlane_b32 s6, v251, 3
	s_waitcnt lgkmcnt(0)
	s_barrier
	s_add_i32 s24, s24, s6
	s_cmpk_gt_i32 s24, 0x7ff
	s_cselect_b64 s[6:7], -1, 0
	s_cmpk_lt_i32 s24, 0x800
	s_cselect_b32 s98, s21, 0
	s_cselect_b32 s99, s22, 0
	s_add_i32 s33, s4, s98
	s_add_i32 s34, s35, s99
	s_and_b32 s8, s33, 0xffffff80
	s_ashr_i32 s9, s8, 31
	s_lshl_b64 s[8:9], s[8:9], 12
	s_add_u32 s8, s14, s8
	s_addc_u32 s9, s20, s9
	s_and_b32 s37, s34, 0x780
	s_lshl_b32 s37, s37, 1
	s_add_u32 s8, s8, s37
	s_addc_u32 s9, s9, 0
	v_lshl_add_u64 v[0:1], v[26:27], 1, s[8:9]
	v_lshl_add_u64 v[4:5], v[24:25], 1, s[8:9]
	v_lshl_add_u64 v[8:9], v[22:23], 1, s[8:9]
	v_lshl_add_u64 v[12:13], v[20:21], 1, s[8:9]
	global_load_dwordx4 v[0:3], v[0:1], off
	s_nop 0
	global_load_dwordx4 v[4:7], v[4:5], off
	s_nop 0
	global_load_dwordx4 v[8:11], v[8:9], off
	s_nop 0
	global_load_dwordx4 v[12:15], v[12:13], off
	s_branch .LBB0_405
